# same as previous best, incremental next-unit index math now guarded by the grid size (generic code kept as fallback)
# baseline (speedup 1.0000x reference)
;     __device__ __forceinline__ size_t a_off(const Unit& u) const { return (size_t)u.pm * atile; }
;     __device__ __forceinline__ size_t b_off(const Unit& u) const { return (size_t)u.pn * btile; }
;     __device__ __forceinline__ size_t a_off(const Unit& u) const { return ((size_t)u.g * NROW + (size_t)u.pm * BM) * KA * 2; }
;     __device__ __forceinline__ size_t b_off(const Unit& u) const { return (size_t)u.g * btile; }
;     __device__ __forceinline__ size_t a_off(const Unit& u) const { return ((size_t)u.g * NROW + (size_t)u.pm * BM) * KA * 2; }
;     __device__ __forceinline__ size_t b_off(const Unit& u) const { return (size_t)u.g * btile; }
; #define PG8_STAGE(bufoff, gbase, voff) do { const __amdgpu_buffer_rsrc_t _r = __builtin_amdgcn_make_buffer_rsrc((void*)(gbase), (short)0, 0x7fffffff, 0x00020000); _Pragma("unroll") for (int _i = 0; _i < 2; ++_i) \
;         __builtin_amdgcn_raw_ptr_buffer_load_lds(_r, (LAS unsigned*)(lds + (bufoff) + ldsw + _i * 8192), 16, (int)(voff)[_i], 0, 0, 0); } while (0)
; #define PG8_WAIT_L(n) asm volatile("s_waitcnt lgkmcnt(" #n ")" ::: "memory")
;     __device__ __forceinline__ bool next(int i, Unit& u) const {
;         const long L = (long)i * G + c; if (L >= nwg) return false;
;         int wgid = (int)L; { const int q = nwg / NXCD, r = nwg % NXCD, xcd = wgid % NXCD, off = wgid / NXCD; wgid = (xcd < r ? xcd * (q + 1) : r * (q + 1) + (xcd - r) * q) + off; }
;         const int nig = WGM * nN, gid = wgid / nig, fm = gid * WGM, gsz = (nM - fm) < WGM ? (nM - fm) : WGM;
;         u.pm = __builtin_amdgcn_readfirstlane(fm + ((wgid % nig) % gsz)); u.pn = __builtin_amdgcn_readfirstlane((wgid % nig) / gsz); u.g = 0; return true;
;     ...
;         const char* nA = has_next ? (const char*)Ap + S.a_off(nxt) : cA; const char* nB = has_next ? (const char*)Btp + S.b_off(nxt) : cB;
;         for (int t = 0; t < nt; t += 2) {
;             const bool last = (t == nt - 2);
;             const char* a1 = cA + (size_t)(t + 1) * kstep;
;             const char* a2 = last ? nA : cA + (size_t)(t + 2) * kstep; const char* b2 = last ? nB : cB + (size_t)(t + 2) * kstep;
;             const char* a3 = a2 + kstep; const char* b3 = b2 + kstep;
;             PG8_LDB(B0, 0, 0); PG8_SCHED; PG8_LDA(At, 0, 0); PG8_STAGE(PG8_SA(1, 1), a1 + hstepA, voffA);
;             PG8_WAIT_L(8); PG8_BAR; PG8_WAIT_L(0); PG8_MMA(0, 0, At, B0); PG8_BAR; PG8_SCHED;
.LBB0_686:
	s_add_i32 s47, s47, 1
	s_mul_i32 s3, s47, s94
	s_mul_hi_u32 s12, s47, s34
	s_add_i32 s3, s12, s3
	s_mul_i32 s12, s47, s34
	s_add_u32 s12, s12, s2
	s_addc_u32 s13, s3, s15
	v_cmp_gt_i64_e32 vcc, s[12:13], v[172:173]
	s_cbranch_vccnz .LBB0_688
	s_cmp_lg_u32 s34, 0x100
	s_cbranch_scc1 .Lnext_gen_17625
	s_add_i32 s52, s72, 4
	s_cmp_ge_i32 s52, 22
	s_cselect_b32 s16, 22, 0
	s_cselect_b32 s17, 8, 0
	s_sub_i32 s52, s52, s16
	s_add_i32 s58, s70, s17
	s_branch .Lnext_done_17625
.Lnext_gen_17625:
	s_ashr_i32 s3, s12, 31
	s_lshr_b32 s3, s3, 29
	s_add_i32 s3, s12, s3
	s_ashr_i32 s16, s3, 3
	s_and_b32 s3, s3, -8
	s_sub_i32 s3, s12, s3
	s_cmp_lt_i32 s3, 0
	s_cselect_b32 s17, s54, 0x160
	s_mul_i32 s3, s3, s17
	s_add_i32 s3, s3, s16
	s_abs_i32 s17, s3
	s_mul_hi_u32 s22, s17, s75
	s_mul_i32 s23, s22, s35
	s_ashr_i32 s16, s3, 31
	s_sub_i32 s17, s17, s23
	s_xor_b32 s16, s16, s49
	s_add_i32 s23, s22, 1
	s_sub_i32 s28, s17, s35
	s_cmp_ge_u32 s17, s35
	s_cselect_b32 s22, s23, s22
	s_cselect_b32 s17, s28, s17
	s_add_i32 s23, s22, 1
	s_cmp_ge_u32 s17, s35
	s_cselect_b32 s17, s23, s22
	s_xor_b32 s17, s17, s16
	s_sub_i32 s16, s17, s16
	s_lshl_b32 s17, s16, 3
	s_sub_i32 s22, 0x80, s17
	s_min_i32 s22, s22, 8
	s_abs_i32 s23, s22
	v_cvt_f32_u32_e32 v0, s23
	s_sub_i32 s29, 0, s23
	s_mul_i32 s16, s16, s33
	s_sub_i32 s3, s3, s16
	v_rcp_iflag_f32_e32 v0, v0
	s_abs_i32 s28, s3
	s_xor_b32 s16, s3, s22
	s_ashr_i32 s16, s16, 31
	v_mul_f32_e32 v0, 0x4f7ffffe, v0
	v_cvt_u32_f32_e32 v0, v0
	s_nop 0
	v_readfirstlane_b32 s30, v0
	s_mul_i32 s29, s29, s30
	s_mul_hi_u32 s29, s30, s29
	s_add_i32 s30, s30, s29
	s_mul_hi_u32 s29, s28, s30
	s_mul_i32 s30, s29, s23
	s_sub_i32 s28, s28, s30
	s_add_i32 s30, s29, 1
	s_sub_i32 s31, s28, s23
	s_cmp_ge_u32 s28, s23
	s_cselect_b32 s29, s30, s29
	s_cselect_b32 s28, s31, s28
	s_add_i32 s30, s29, 1
	s_cmp_ge_u32 s28, s23
	s_cselect_b32 s23, s30, s29
	s_xor_b32 s23, s23, s16
	s_sub_i32 s52, s23, s16
	s_mul_i32 s16, s52, s22
	s_sub_i32 s3, s3, s16
	s_add_i32 s58, s3, s17
.Lnext_done_17625:
.LBB0_688:
	s_ashr_i32 s59, s58, 31
	s_lshl_b64 s[16:17], s[58:59], 19
	s_add_u32 s64, s20, s16
	s_addc_u32 s65, s21, s17
	s_ashr_i32 s53, s52, 31
	s_lshl_b64 s[16:17], s[52:53], 19
	s_add_u32 s66, s76, s16
	v_cmp_lt_i64_e64 s[12:13], s[12:13], v[170:171]
	s_addc_u32 s67, s77, s17
	s_andn2_b64 vcc, exec, s[50:51]
	s_cbranch_vccnz .Lkzero_690
	s_and_b64 s[16:17], s[12:13], exec
	s_cselect_b32 s53, s65, s27
	s_cselect_b32 s59, s64, s26
	s_cselect_b32 s96, s67, s25
	s_cselect_b32 s97, s66, s24
	s_add_u32 vcc_lo, s26, 0x100
	s_addc_u32 vcc_hi, s27, 0
	s_add_u32 s3, s24, 0x100
	s_addc_u32 s46, s25, 0
	s_mov_b32 s16, 0
	ds_read_b128 v[76:79], v193
	ds_read_b128 v[88:91], v193 offset:1024
	ds_read_b128 v[92:95], v193 offset:2048
	ds_read_b128 v[128:131], v193 offset:3072
	s_add_i32 s22, s16, 2
	s_cmp_eq_u32 s91, s16
	s_cselect_b32 s36, s59, vcc_lo
	s_cselect_b32 s26, s53, vcc_hi
	s_cselect_b32 s25, s96, s46
	s_cselect_b32 s28, s97, s3
	s_add_u32 s24, s36, 0x80
	s_addc_u32 s23, s26, 0
	s_add_u32 s16, vcc_lo, s0
	s_addc_u32 s17, vcc_hi, s1
	s_add_u32 s16, s16, 0xffffff80
	s_addc_u32 s17, s17, -1
	s_and_b32 s17, s17, 0xffff
	s_mov_b32 m0, s92
	ds_read_b128 v[132:135], v194
	ds_read_b128 v[136:139], v194 offset:1024
	ds_read_b128 v[140:143], v194 offset:2048
	ds_read_b128 v[174:177], v194 offset:3072
	ds_read_b128 v[178:181], v194 offset:4096
	ds_read_b128 v[182:185], v194 offset:5120
	ds_read_b128 v[202:205], v194 offset:6144
	ds_read_b128 v[206:209], v194 offset:7168
	buffer_load_dwordx4 v186, s[16:19], 0 offen lds
	s_mov_b32 m0, s93
	s_nop 0
	buffer_load_dwordx4 v188, s[16:19], 0 offen lds
	s_waitcnt lgkmcnt(8)
	s_barrier
	s_waitcnt lgkmcnt(0)
	s_setprio 1
	s_waitcnt lgkmcnt(7)
	v_mfma_f32_16x16x32_bf16 v[152:155], v[76:79], v[132:135], 0
	v_mfma_f32_16x16x32_bf16 v[144:147], v[92:95], v[132:135], 0
	s_waitcnt lgkmcnt(5)
	v_mfma_f32_16x16x32_bf16 v[124:127], v[76:79], v[140:143], 0
	v_mfma_f32_16x16x32_bf16 v[120:123], v[92:95], v[140:143], 0
	s_waitcnt lgkmcnt(3)
	v_mfma_f32_16x16x32_bf16 v[108:111], v[76:79], v[178:181], 0
	v_mfma_f32_16x16x32_bf16 v[104:107], v[92:95], v[178:181], 0
	s_waitcnt lgkmcnt(1)
	v_mfma_f32_16x16x32_bf16 v[84:87], v[76:79], v[202:205], 0
	v_mfma_f32_16x16x32_bf16 v[80:83], v[92:95], v[202:205], 0
	v_mfma_f32_16x16x32_bf16 v[152:155], v[88:91], v[136:139], v[152:155]
	v_mfma_f32_16x16x32_bf16 v[144:147], v[128:131], v[136:139], v[144:147]
	v_mfma_f32_16x16x32_bf16 v[124:127], v[88:91], v[174:177], v[124:127]
	v_mfma_f32_16x16x32_bf16 v[120:123], v[128:131], v[174:177], v[120:123]
	v_mfma_f32_16x16x32_bf16 v[108:111], v[88:91], v[182:185], v[108:111]
	v_mfma_f32_16x16x32_bf16 v[104:107], v[128:131], v[182:185], v[104:107]
	s_waitcnt lgkmcnt(0)
	v_mfma_f32_16x16x32_bf16 v[84:87], v[88:91], v[206:209], v[84:87]
	v_mfma_f32_16x16x32_bf16 v[80:83], v[128:131], v[206:209], v[80:83]
	s_setprio 0
	s_barrier
; #define PG8_STAGE(bufoff, gbase, voff) do { const __amdgpu_buffer_rsrc_t _r = __builtin_amdgcn_make_buffer_rsrc((void*)(gbase), (short)0, 0x7fffffff, 0x00020000); _Pragma("unroll") for (int _i = 0; _i < 2; ++_i) \
;         __builtin_amdgcn_raw_ptr_buffer_load_lds(_r, (LAS unsigned*)(lds + (bufoff) + ldsw + _i * 8192), 16, (int)(voff)[_i], 0, 0, 0); } while (0)
; #define PG8_LDA(dst, b, h) do { _Pragma("unroll") for (int m = 0; m < 4; ++m) _Pragma("unroll") for (int k = 0; k < 2; ++k) dst[m][k] = *(const LAS bf16x8*)(lds + PG8_SA(b, h) + aoff + m * 2048 + k * 1024); } while (0)
; #define PG8_LDB(dst, b, h) do { _Pragma("unroll") for (int n = 0; n < 2; ++n) _Pragma("unroll") for (int k = 0; k < 2; ++k) dst[n][k] = *(const LAS bf16x8*)(lds + PG8_SB(b, h) + boff + n * 2048 + k * 1024); } while (0)
; #define PG8_MMA(ai, bj, At, Bt) do { __builtin_amdgcn_s_setprio(1); _Pragma("unroll") for (int k = 0; k < 2; ++k) _Pragma("unroll") for (int m = 0; m < 4; ++m) _Pragma("unroll") for (int n = 0; n < ((bj) == 1 ? NB1 : 2); ++n) \
;         acc[ai][bj][m][n] = __builtin_amdgcn_mfma_f32_16x16x32_bf16(Bt[n][k], At[m][k], acc[ai][bj][m][n], 0, 0, 0); __builtin_amdgcn_s_setprio(0); } while (0)
; #define PG8_WAIT_V(n) asm volatile("s_waitcnt vmcnt(" #n ")" ::: "memory")
; #define PG8_WAIT_L(n) asm volatile("s_waitcnt lgkmcnt(" #n ")" ::: "memory")
;     ...
;             PG8_LDB(B1, 0, 1); PG8_STAGE(PG8_SB(0, 0), b2, voffB);
;             PG8_BAR; PG8_WAIT_L(0); PG8_MMA(0, 1, At, B1); PG8_BAR;
;             PG8_LDA(At, 0, 1); PG8_STAGE(PG8_SA(0, 0), a2, voffA);
;             PG8_BAR; PG8_WAIT_L(0); PG8_MMA(1, 0, At, B0); PG8_BAR; PG8_SCHED;
;             PG8_STAGE(PG8_SB(0, 1), b2 + hstepB, voffB);
;             PG8_WAIT_V(6); PG8_BAR; PG8_MMA(1, 1, At, B1); PG8_BAR;
;             PG8_LDB(B0, 1, 0); PG8_SCHED; PG8_LDA(At, 1, 0); PG8_STAGE(PG8_SA(0, 1), a2 + hstepA, voffA);
;             PG8_WAIT_L(8); PG8_BAR; PG8_WAIT_L(0); PG8_MMA(0, 0, At, B0); PG8_BAR; PG8_SCHED;
;             PG8_LDB(B1, 1, 1); PG8_STAGE(PG8_SB(1, 0), b3, voffB);
;             PG8_BAR; PG8_WAIT_L(0); PG8_MMA(0, 1, At, B1); PG8_BAR;
;             PG8_LDA(At, 1, 1); PG8_STAGE(PG8_SA(1, 0), a3, voffA);
;             PG8_BAR; PG8_WAIT_L(0); PG8_MMA(1, 0, At, B0); PG8_BAR; PG8_SCHED;
;             PG8_STAGE(PG8_SB(1, 1), b3 + hstepB, voffB);
;             PG8_WAIT_V(6); PG8_BAR; PG8_MMA(1, 1, At, B1); PG8_BAR;
	s_and_b32 s29, s25, 0xffff
	s_mov_b32 s30, s18
	s_mov_b32 s31, s19
	s_mov_b32 m0, s73
	ds_read_b128 v[210:213], v195
	ds_read_b128 v[214:217], v195 offset:1024
	ds_read_b128 v[218:221], v195 offset:2048
	ds_read_b128 v[222:225], v195 offset:3072
	buffer_load_dwordx4 v187, s[28:31], 0 offen lds
	s_mov_b32 m0, s78
	s_nop 0
	buffer_load_dwordx4 v189, s[28:31], 0 offen lds
	s_barrier
	s_waitcnt lgkmcnt(0)
	s_setprio 1
	s_waitcnt lgkmcnt(3)
	v_mfma_f32_16x16x32_bf16 v[116:119], v[210:213], v[140:143], 0
	s_waitcnt lgkmcnt(1)
	v_mfma_f32_16x16x32_bf16 v[112:115], v[218:221], v[140:143], 0
	v_mfma_f32_16x16x32_bf16 v[100:103], v[210:213], v[178:181], 0
	v_mfma_f32_16x16x32_bf16 v[96:99], v[218:221], v[178:181], 0
	v_mfma_f32_16x16x32_bf16 v[68:71], v[210:213], v[202:205], 0
	v_mfma_f32_16x16x32_bf16 v[64:67], v[218:221], v[202:205], 0
	v_mfma_f32_16x16x32_bf16 v[156:159], v[210:213], v[132:135], 0
	v_mfma_f32_16x16x32_bf16 v[132:135], v[218:221], v[132:135], 0
	v_mfma_f32_16x16x32_bf16 v[116:119], v[214:217], v[174:177], v[116:119]
	s_waitcnt lgkmcnt(0)
	v_mfma_f32_16x16x32_bf16 v[112:115], v[222:225], v[174:177], v[112:115]
	v_mfma_f32_16x16x32_bf16 v[100:103], v[214:217], v[182:185], v[100:103]
	v_mfma_f32_16x16x32_bf16 v[96:99], v[222:225], v[182:185], v[96:99]
	v_mfma_f32_16x16x32_bf16 v[68:71], v[214:217], v[206:209], v[68:71]
	v_mfma_f32_16x16x32_bf16 v[64:67], v[222:225], v[206:209], v[64:67]
	v_mfma_f32_16x16x32_bf16 v[140:143], v[214:217], v[136:139], v[156:159]
	v_mfma_f32_16x16x32_bf16 v[132:135], v[222:225], v[136:139], v[132:135]
	s_setprio 0
	s_and_b32 s37, s26, 0xffff
	s_mov_b32 s38, s18
	s_mov_b32 s39, s19
	s_mov_b32 m0, s71
	s_barrier
	ds_read_b128 v[136:139], v194 offset:16384
	ds_read_b128 v[148:151], v194 offset:17408
	ds_read_b128 v[156:159], v194 offset:18432
	ds_read_b128 v[174:177], v194 offset:19456
	ds_read_b128 v[178:181], v194 offset:20480
	ds_read_b128 v[182:185], v194 offset:21504
	ds_read_b128 v[202:205], v194 offset:22528
	ds_read_b128 v[206:209], v194 offset:23552
	buffer_load_dwordx4 v186, s[36:39], 0 offen lds
	s_mov_b32 m0, s79
	s_nop 0
	buffer_load_dwordx4 v188, s[36:39], 0 offen lds
	s_barrier
	s_waitcnt lgkmcnt(0)
	s_setprio 1
	s_waitcnt lgkmcnt(7)
	v_mfma_f32_16x16x32_bf16 v[60:63], v[76:79], v[136:139], 0
	v_mfma_f32_16x16x32_bf16 v[52:55], v[92:95], v[136:139], 0
	s_waitcnt lgkmcnt(5)
	v_mfma_f32_16x16x32_bf16 v[44:47], v[76:79], v[156:159], 0
	v_mfma_f32_16x16x32_bf16 v[40:43], v[92:95], v[156:159], 0
	s_waitcnt lgkmcnt(3)
	v_mfma_f32_16x16x32_bf16 v[28:31], v[76:79], v[178:181], 0
	v_mfma_f32_16x16x32_bf16 v[24:27], v[92:95], v[178:181], 0
	s_waitcnt lgkmcnt(1)
	v_mfma_f32_16x16x32_bf16 v[12:15], v[76:79], v[202:205], 0
	v_mfma_f32_16x16x32_bf16 v[8:11], v[92:95], v[202:205], 0
	v_mfma_f32_16x16x32_bf16 v[60:63], v[88:91], v[148:151], v[60:63]
	v_mfma_f32_16x16x32_bf16 v[52:55], v[128:131], v[148:151], v[52:55]
	v_mfma_f32_16x16x32_bf16 v[44:47], v[88:91], v[174:177], v[44:47]
	v_mfma_f32_16x16x32_bf16 v[40:43], v[128:131], v[174:177], v[40:43]
	v_mfma_f32_16x16x32_bf16 v[28:31], v[88:91], v[182:185], v[28:31]
	v_mfma_f32_16x16x32_bf16 v[24:27], v[128:131], v[182:185], v[24:27]
	s_waitcnt lgkmcnt(0)
	v_mfma_f32_16x16x32_bf16 v[12:15], v[88:91], v[206:209], v[12:15]
	v_mfma_f32_16x16x32_bf16 v[8:11], v[128:131], v[206:209], v[8:11]
	s_setprio 0
	s_barrier
	s_add_u32 s16, s28, s44
	s_addc_u32 s74, s25, s45
	s_and_b32 s17, s74, 0xffff
	s_mov_b32 m0, s80
	s_nop 0
	buffer_load_dwordx4 v187, s[16:19], 0 offen lds
	s_mov_b32 m0, s81
	s_nop 0
	buffer_load_dwordx4 v189, s[16:19], 0 offen lds
	s_waitcnt vmcnt(6)
	s_barrier
	s_setprio 1
	v_mfma_f32_16x16x32_bf16 v[56:59], v[210:213], v[136:139], 0
	v_mfma_f32_16x16x32_bf16 v[48:51], v[218:221], v[136:139], 0
	v_mfma_f32_16x16x32_bf16 v[36:39], v[210:213], v[156:159], 0
	v_mfma_f32_16x16x32_bf16 v[32:35], v[218:221], v[156:159], 0
	v_mfma_f32_16x16x32_bf16 v[20:23], v[210:213], v[178:181], 0
	v_mfma_f32_16x16x32_bf16 v[16:19], v[218:221], v[178:181], 0
	v_mfma_f32_16x16x32_bf16 v[4:7], v[210:213], v[202:205], 0
	v_mfma_f32_16x16x32_bf16 v[0:3], v[218:221], v[202:205], 0
	v_mfma_f32_16x16x32_bf16 v[56:59], v[214:217], v[148:151], v[56:59]
	v_mfma_f32_16x16x32_bf16 v[48:51], v[222:225], v[148:151], v[48:51]
	v_mfma_f32_16x16x32_bf16 v[36:39], v[214:217], v[174:177], v[36:39]
	v_mfma_f32_16x16x32_bf16 v[32:35], v[222:225], v[174:177], v[32:35]
	v_mfma_f32_16x16x32_bf16 v[20:23], v[214:217], v[182:185], v[20:23]
	v_mfma_f32_16x16x32_bf16 v[16:19], v[222:225], v[182:185], v[16:19]
	v_mfma_f32_16x16x32_bf16 v[4:7], v[214:217], v[206:209], v[4:7]
	v_mfma_f32_16x16x32_bf16 v[0:3], v[222:225], v[206:209], v[0:3]
	s_setprio 0
	s_barrier
	s_branch .Lkmid_690

;     __device__ __forceinline__ bool next(int i, Unit& u) const {
;         const long L = (long)i * G + c; if (L >= nwg) return false;
;         int wgid = (int)L; { const int q = nwg / NXCD, r = nwg % NXCD, xcd = wgid % NXCD, off = wgid / NXCD; wgid = (xcd < r ? xcd * (q + 1) : r * (q + 1) + (xcd - r) * q) + off; }
;         const int nig = WGM * nN, gid = wgid / nig, fm = gid * WGM, gsz = (nM - fm) < WGM ? (nM - fm) : WGM;
;         u.pm = __builtin_amdgcn_readfirstlane(fm + ((wgid % nig) % gsz)); u.pn = __builtin_amdgcn_readfirstlane((wgid % nig) / gsz); u.g = 0; return true;
.LBB0_836:
	s_add_i32 s47, s47, 1
	s_mul_i32 s12, s47, s3
	s_mul_hi_u32 s13, s47, s34
	s_add_i32 s13, s13, s12
	s_mul_i32 s12, s47, s34
	s_add_u32 s12, s12, s2
	s_addc_u32 s13, s13, s90
	v_cmp_gt_i64_e32 vcc, s[12:13], v[120:121]
	s_cbranch_vccnz .LBB0_842
	s_cmp_lg_u32 s34, 0x100
	s_cbranch_scc1 .Lnext_gen_23079
	s_add_i32 s52, s72, 4
	s_cmp_ge_i32 s52, 16
	s_cselect_b32 s16, 16, 0
	s_cselect_b32 s17, 8, 0
	s_sub_i32 s52, s52, s16
	s_add_i32 s58, s70, s17
	s_branch .Lnext_done_23079
.Lnext_gen_23079:
	s_ashr_i32 s16, s12, 31
	s_lshr_b32 s16, s16, 29
	s_add_i32 s22, s12, s16
	s_and_b32 s16, s22, -8
	s_sub_i32 s23, s12, s16
	s_cmp_gt_i32 s23, -1
	s_mov_b64 s[16:17], -1
	s_cbranch_scc0 .LBB0_839
	s_lshl_b32 s28, s23, 8
	s_mov_b64 s[16:17], 0

;     __device__ __forceinline__ size_t a_off(const Unit& u) const { return (size_t)u.pm * atile; }
;     __device__ __forceinline__ size_t b_off(const Unit& u) const { return (size_t)u.pn * btile; }
;     __device__ __forceinline__ size_t a_off(const Unit& u) const { return ((size_t)u.g * NROW + (size_t)u.pm * BM) * KA * 2; }
;     __device__ __forceinline__ size_t b_off(const Unit& u) const { return (size_t)u.g * btile; }
;     __device__ __forceinline__ size_t a_off(const Unit& u) const { return ((size_t)u.g * NROW + (size_t)u.pm * BM) * KA * 2; }
;     __device__ __forceinline__ size_t b_off(const Unit& u) const { return (size_t)u.g * btile; }
;     ...
;         const char* nA = has_next ? (const char*)Ap + S.a_off(nxt) : cA; const char* nB = has_next ? (const char*)Btp + S.b_off(nxt) : cB;
;         for (int t = 0; t < nt; t += 2) {
;             const bool last = (t == nt - 2);
;             const char* a1 = cA + (size_t)(t + 1) * kstep;
;             const char* a2 = last ? nA : cA + (size_t)(t + 2) * kstep; const char* b2 = last ? nB : cB + (size_t)(t + 2) * kstep;
;             const char* a3 = a2 + kstep; const char* b3 = b2 + kstep;
;             PG8_LDB(B0, 0, 0); PG8_SCHED; PG8_LDA(At, 0, 0); PG8_STAGE(PG8_SA(1, 1), a1 + hstepA, voffA);
;             PG8_WAIT_L(8); PG8_BAR; PG8_WAIT_L(0); PG8_MMA(0, 0, At, B0); PG8_BAR; PG8_SCHED;
;             PG8_LDB(B1, 0, 1); PG8_STAGE(PG8_SB(0, 0), b2, voffB);
;             PG8_BAR; PG8_WAIT_L(0); PG8_MMA(0, 1, At, B1); PG8_BAR;
;             PG8_LDA(At, 0, 1); PG8_STAGE(PG8_SA(0, 0), a2, voffA);
;             PG8_BAR; PG8_WAIT_L(0); PG8_MMA(1, 0, At, B0); PG8_BAR; PG8_SCHED;
;             PG8_STAGE(PG8_SB(0, 1), b2 + hstepB, voffB);
;             PG8_WAIT_V(6); PG8_BAR; PG8_MMA(1, 1, At, B1); PG8_BAR;
;             PG8_LDB(B0, 1, 0); PG8_SCHED; PG8_LDA(At, 1, 0); PG8_STAGE(PG8_SA(0, 1), a2 + hstepA, voffA);
;             PG8_WAIT_L(8); PG8_BAR; PG8_WAIT_L(0); PG8_MMA(0, 0, At, B0); PG8_BAR; PG8_SCHED;
;             PG8_LDB(B1, 1, 1); PG8_STAGE(PG8_SB(1, 0), b3, voffB);
;             PG8_BAR; PG8_WAIT_L(0); PG8_MMA(0, 1, At, B1); PG8_BAR;
;             PG8_LDA(At, 1, 1); PG8_STAGE(PG8_SA(1, 0), a3, voffA);
;             PG8_BAR; PG8_WAIT_L(0); PG8_MMA(1, 0, At, B0); PG8_BAR; PG8_SCHED;
;             PG8_STAGE(PG8_SB(1, 1), b3 + hstepB, voffB);
;             PG8_WAIT_V(6); PG8_BAR; PG8_MMA(1, 1, At, B1); PG8_BAR;
.Lnext_done_23079:
.LBB0_842:
	s_ashr_i32 s59, s58, 31
	s_lshl_b64 s[16:17], s[58:59], 19
	s_add_u32 s64, s20, s16
	s_addc_u32 s65, s21, s17
	s_ashr_i32 s53, s52, 31
	s_lshl_b64 s[16:17], s[52:53], 19
	s_add_u32 s66, s33, s16
	v_cmp_lt_i64_e64 s[12:13], s[12:13], v[118:119]
	s_addc_u32 s67, s35, s17
	s_andn2_b64 vcc, exec, s[68:69]
	s_cbranch_vccnz .Lkzero_844
	s_and_b64 s[16:17], s[12:13], exec
	s_cselect_b32 s22, s65, s27
	s_cselect_b32 s23, s64, s26
	s_cselect_b32 s53, s67, s25
	s_cselect_b32 s59, s66, s24
	s_add_u32 s94, s26, 0x100
	s_addc_u32 s95, s27, 0
	s_add_u32 s96, s24, 0x100
	s_addc_u32 s97, s25, 0
	s_mov_b32 s16, 0
	ds_read_b128 v[100:103], v141
	ds_read_b128 v[104:107], v141 offset:1024
	ds_read_b128 v[122:125], v141 offset:2048
	ds_read_b128 v[126:129], v141 offset:3072
	s_add_i32 vcc_lo, s16, 2
	s_cmp_eq_u32 s87, s16
	s_cselect_b32 s36, s23, s94
	s_cselect_b32 s26, s22, s95
	s_cselect_b32 s27, s53, s97
	s_cselect_b32 s28, s59, s96
	s_add_u32 s24, s36, 0x80
	s_addc_u32 s25, s26, 0
	s_add_u32 s16, s94, s0
	s_addc_u32 s17, s95, s1
	s_add_u32 s16, s16, 0xffffff80
	s_addc_u32 s17, s17, -1
	s_and_b32 s17, s17, 0xffff
	s_mov_b32 m0, s88
	ds_read_b128 v[130:133], v142
	ds_read_b128 v[150:153], v142 offset:1024
	ds_read_b128 v[154:157], v142 offset:2048
	ds_read_b128 v[158:161], v142 offset:3072
	ds_read_b128 v[162:165], v142 offset:4096
	ds_read_b128 v[166:169], v142 offset:5120
	ds_read_b128 v[170:173], v142 offset:6144
	ds_read_b128 v[174:177], v142 offset:7168
	buffer_load_dwordx4 v134, s[16:19], 0 offen lds
	s_mov_b32 m0, s89
	s_nop 0
	buffer_load_dwordx4 v136, s[16:19], 0 offen lds
	s_waitcnt lgkmcnt(8)
	s_barrier
	s_waitcnt lgkmcnt(0)
	s_setprio 1
	s_waitcnt lgkmcnt(7)
	v_mfma_f32_16x16x32_bf16 v[88:91], v[100:103], v[130:133], 0
	v_mfma_f32_16x16x32_bf16 v[96:99], v[122:125], v[130:133], 0
	s_waitcnt lgkmcnt(5)
	v_mfma_f32_16x16x32_bf16 v[76:79], v[100:103], v[154:157], 0
	v_mfma_f32_16x16x32_bf16 v[84:87], v[122:125], v[154:157], 0
	s_waitcnt lgkmcnt(3)
	v_mfma_f32_16x16x32_bf16 v[64:67], v[100:103], v[162:165], 0
	v_mfma_f32_16x16x32_bf16 v[72:75], v[122:125], v[162:165], 0
	s_waitcnt lgkmcnt(1)
	v_mfma_f32_16x16x32_bf16 v[52:55], v[100:103], v[170:173], 0
	v_mfma_f32_16x16x32_bf16 v[60:63], v[122:125], v[170:173], 0
	v_mfma_f32_16x16x32_bf16 v[88:91], v[104:107], v[150:153], v[88:91]
	v_mfma_f32_16x16x32_bf16 v[96:99], v[126:129], v[150:153], v[96:99]
	v_mfma_f32_16x16x32_bf16 v[76:79], v[104:107], v[158:161], v[76:79]
	v_mfma_f32_16x16x32_bf16 v[84:87], v[126:129], v[158:161], v[84:87]
	v_mfma_f32_16x16x32_bf16 v[64:67], v[104:107], v[166:169], v[64:67]
	v_mfma_f32_16x16x32_bf16 v[72:75], v[126:129], v[166:169], v[72:75]
	s_waitcnt lgkmcnt(0)
	v_mfma_f32_16x16x32_bf16 v[52:55], v[104:107], v[174:177], v[52:55]
	v_mfma_f32_16x16x32_bf16 v[60:63], v[126:129], v[174:177], v[60:63]
	s_setprio 0
	s_barrier
	s_and_b32 s29, s27, 0xffff
	s_mov_b32 s30, s18
	s_mov_b32 s31, s19
	s_mov_b32 m0, s73
	ds_read_b128 v[178:181], v143
	ds_read_b128 v[182:185], v143 offset:1024
	buffer_load_dwordx4 v135, s[28:31], 0 offen lds
	s_mov_b32 m0, s74
	s_nop 0
	buffer_load_dwordx4 v137, s[28:31], 0 offen lds
	s_barrier
	s_waitcnt lgkmcnt(0)
	s_setprio 1
	s_waitcnt lgkmcnt(1)
	v_mfma_f32_16x16x32_bf16 v[92:95], v[178:181], v[130:133], 0
	v_mfma_f32_16x16x32_bf16 v[80:83], v[178:181], v[154:157], 0
	v_mfma_f32_16x16x32_bf16 v[68:71], v[178:181], v[162:165], 0
	v_mfma_f32_16x16x32_bf16 v[56:59], v[178:181], v[170:173], 0
	s_waitcnt lgkmcnt(0)
	v_mfma_f32_16x16x32_bf16 v[92:95], v[182:185], v[150:153], v[92:95]
	v_mfma_f32_16x16x32_bf16 v[80:83], v[182:185], v[158:161], v[80:83]
	v_mfma_f32_16x16x32_bf16 v[68:71], v[182:185], v[166:169], v[68:71]
	v_mfma_f32_16x16x32_bf16 v[56:59], v[182:185], v[174:177], v[56:59]
	s_setprio 0
	s_and_b32 s37, s26, 0xffff
	s_mov_b32 s38, s18
	s_mov_b32 s39, s19
	s_mov_b32 m0, s71
	s_barrier
	ds_read_b128 v[130:133], v142 offset:16384
	ds_read_b128 v[150:153], v142 offset:17408
	ds_read_b128 v[154:157], v142 offset:18432
	ds_read_b128 v[158:161], v142 offset:19456
	ds_read_b128 v[162:165], v142 offset:20480
	ds_read_b128 v[166:169], v142 offset:21504
	ds_read_b128 v[170:173], v142 offset:22528
	ds_read_b128 v[174:177], v142 offset:23552
	buffer_load_dwordx4 v134, s[36:39], 0 offen lds
	s_mov_b32 m0, s75
	s_nop 0
	buffer_load_dwordx4 v136, s[36:39], 0 offen lds
	s_barrier
	s_waitcnt lgkmcnt(0)
	s_setprio 1
	s_waitcnt lgkmcnt(7)
	v_mfma_f32_16x16x32_bf16 v[44:47], v[100:103], v[130:133], 0
	v_mfma_f32_16x16x32_bf16 v[48:51], v[122:125], v[130:133], 0
	s_waitcnt lgkmcnt(5)
	v_mfma_f32_16x16x32_bf16 v[28:31], v[100:103], v[154:157], 0
	v_mfma_f32_16x16x32_bf16 v[36:39], v[122:125], v[154:157], 0
	s_waitcnt lgkmcnt(3)
	v_mfma_f32_16x16x32_bf16 v[12:15], v[100:103], v[162:165], 0
	v_mfma_f32_16x16x32_bf16 v[20:23], v[122:125], v[162:165], 0
	s_waitcnt lgkmcnt(1)
	v_mfma_f32_16x16x32_bf16 v[0:3], v[100:103], v[170:173], 0
	v_mfma_f32_16x16x32_bf16 v[8:11], v[122:125], v[170:173], 0
	v_mfma_f32_16x16x32_bf16 v[44:47], v[104:107], v[150:153], v[44:47]
	v_mfma_f32_16x16x32_bf16 v[48:51], v[126:129], v[150:153], v[48:51]
	v_mfma_f32_16x16x32_bf16 v[28:31], v[104:107], v[158:161], v[28:31]
	v_mfma_f32_16x16x32_bf16 v[36:39], v[126:129], v[158:161], v[36:39]
	v_mfma_f32_16x16x32_bf16 v[12:15], v[104:107], v[166:169], v[12:15]
	v_mfma_f32_16x16x32_bf16 v[20:23], v[126:129], v[166:169], v[20:23]
	s_waitcnt lgkmcnt(0)
	v_mfma_f32_16x16x32_bf16 v[0:3], v[104:107], v[174:177], v[0:3]
	v_mfma_f32_16x16x32_bf16 v[8:11], v[126:129], v[174:177], v[8:11]
	s_setprio 0
	s_barrier
	s_add_u32 s16, s28, s44
	s_addc_u32 vcc_hi, s27, s45
	s_and_b32 s17, vcc_hi, 0xffff
	s_mov_b32 m0, s76
	s_nop 0
	buffer_load_dwordx4 v135, s[16:19], 0 offen lds
	s_mov_b32 m0, s77
	s_nop 0
	buffer_load_dwordx4 v137, s[16:19], 0 offen lds
	s_waitcnt vmcnt(6)
	s_barrier
	s_setprio 1
	v_mfma_f32_16x16x32_bf16 v[40:43], v[178:181], v[130:133], 0
	v_mfma_f32_16x16x32_bf16 v[32:35], v[178:181], v[154:157], 0
	v_mfma_f32_16x16x32_bf16 v[16:19], v[178:181], v[162:165], 0
	v_mfma_f32_16x16x32_bf16 v[4:7], v[178:181], v[170:173], 0
	v_mfma_f32_16x16x32_bf16 v[40:43], v[182:185], v[150:153], v[40:43]
	v_mfma_f32_16x16x32_bf16 v[32:35], v[182:185], v[158:161], v[32:35]
	v_mfma_f32_16x16x32_bf16 v[16:19], v[182:185], v[166:169], v[16:19]
	v_mfma_f32_16x16x32_bf16 v[4:7], v[182:185], v[174:177], v[4:7]
	s_setprio 0
	s_barrier
	s_branch .Lkmid_844

;     __device__ __forceinline__ size_t a_off(const Unit& u) const { return (size_t)u.pm * atile; }
;     __device__ __forceinline__ size_t b_off(const Unit& u) const { return (size_t)u.pn * btile; }
;     __device__ __forceinline__ size_t a_off(const Unit& u) const { return ((size_t)u.g * NROW + (size_t)u.pm * BM) * KA * 2; }
;     __device__ __forceinline__ size_t b_off(const Unit& u) const { return (size_t)u.g * btile; }
;     __device__ __forceinline__ size_t a_off(const Unit& u) const { return ((size_t)u.g * NROW + (size_t)u.pm * BM) * KA * 2; }
;     __device__ __forceinline__ size_t b_off(const Unit& u) const { return (size_t)u.g * btile; }
; #define PG8_STAGE(bufoff, gbase, voff) do { const __amdgpu_buffer_rsrc_t _r = __builtin_amdgcn_make_buffer_rsrc((void*)(gbase), (short)0, 0x7fffffff, 0x00020000); _Pragma("unroll") for (int _i = 0; _i < 2; ++_i) \
;         __builtin_amdgcn_raw_ptr_buffer_load_lds(_r, (LAS unsigned*)(lds + (bufoff) + ldsw + _i * 8192), 16, (int)(voff)[_i], 0, 0, 0); } while (0)
; #define PG8_WAIT_L(n) asm volatile("s_waitcnt lgkmcnt(" #n ")" ::: "memory")
;     __device__ __forceinline__ bool next(int i, Unit& u) const {
;         const long L = (long)i * G + c; if (L >= nwg) return false;
;         int wgid = (int)L; { const int q = nwg / NXCD, r = nwg % NXCD, xcd = wgid % NXCD, off = wgid / NXCD; wgid = (xcd < r ? xcd * (q + 1) : r * (q + 1) + (xcd - r) * q) + off; }
;         const int nig = WGM * nN, gid = wgid / nig, fm = gid * WGM, gsz = (nM - fm) < WGM ? (nM - fm) : WGM;
;         u.pm = __builtin_amdgcn_readfirstlane(fm + ((wgid % nig) % gsz)); u.pn = __builtin_amdgcn_readfirstlane((wgid % nig) / gsz); u.g = 0; return true;
;     ...
;         const char* nA = has_next ? (const char*)Ap + S.a_off(nxt) : cA; const char* nB = has_next ? (const char*)Btp + S.b_off(nxt) : cB;
;         for (int t = 0; t < nt; t += 2) {
;             const bool last = (t == nt - 2);
;             const char* a1 = cA + (size_t)(t + 1) * kstep;
;             const char* a2 = last ? nA : cA + (size_t)(t + 2) * kstep; const char* b2 = last ? nB : cB + (size_t)(t + 2) * kstep;
;             const char* a3 = a2 + kstep; const char* b3 = b2 + kstep;
;             PG8_LDB(B0, 0, 0); PG8_SCHED; PG8_LDA(At, 0, 0); PG8_STAGE(PG8_SA(1, 1), a1 + hstepA, voffA);
;             PG8_WAIT_L(8); PG8_BAR; PG8_WAIT_L(0); PG8_MMA(0, 0, At, B0); PG8_BAR; PG8_SCHED;
.LBB0_980:
	s_add_i32 s49, s49, 1
	s_mul_i32 s12, s49, s3
	s_mul_hi_u32 s13, s49, s34
	s_add_i32 s13, s13, s12
	s_mul_i32 s12, s49, s34
	s_add_u32 s12, s12, s2
	s_addc_u32 s13, s13, s33
	v_cmp_gt_i64_e32 vcc, s[12:13], v[172:173]
	s_cbranch_vccnz .LBB0_982
	s_cmp_lg_u32 s34, 0x100
	s_cbranch_scc1 .Lnext_gen_28037
	s_add_i32 s52, s70, 4
	s_cmp_ge_i32 s52, 22
	s_cselect_b32 s16, 22, 0
	s_cselect_b32 s17, 8, 0
	s_sub_i32 s52, s52, s16
	s_add_i32 s56, s66, s17
	s_branch .Lnext_done_28037
.Lnext_gen_28037:
	s_ashr_i32 s16, s12, 31
	s_lshr_b32 s16, s16, 29
	s_add_i32 s16, s12, s16
	s_ashr_i32 s17, s16, 3
	s_and_b32 s16, s16, -8
	s_sub_i32 s16, s12, s16
	s_cmp_lt_i32 s16, 0
	s_cselect_b32 s22, s48, 0x160
	s_mul_i32 s16, s16, s22
	s_add_i32 s16, s16, s17
	s_abs_i32 s22, s16
	s_mul_hi_u32 s23, s22, s74
	s_mul_i32 s28, s23, s72
	s_ashr_i32 s17, s16, 31
	s_sub_i32 s22, s22, s28
	s_xor_b32 s17, s17, s73
	s_add_i32 s28, s23, 1
	s_sub_i32 s29, s22, s72
	s_cmp_ge_u32 s22, s72
	s_cselect_b32 s23, s28, s23
	s_cselect_b32 s22, s29, s22
	s_add_i32 s28, s23, 1
	s_cmp_ge_u32 s22, s72
	s_cselect_b32 s22, s28, s23
	s_xor_b32 s22, s22, s17
	s_sub_i32 s17, s22, s17
	s_lshl_b32 s22, s17, 3
	s_sub_i32 s23, 0x80, s22
	s_min_i32 s23, s23, 8
	s_abs_i32 s28, s23
	v_cvt_f32_u32_e32 v0, s28
	s_sub_i32 s30, 0, s28
	s_mul_i32 s17, s17, s35
	s_sub_i32 s16, s16, s17
	v_rcp_iflag_f32_e32 v0, v0
	s_abs_i32 s29, s16
	s_xor_b32 s17, s16, s23
	s_ashr_i32 s17, s17, 31
	v_mul_f32_e32 v0, 0x4f7ffffe, v0
	v_cvt_u32_f32_e32 v0, v0
	s_nop 0
	v_readfirstlane_b32 s31, v0
	s_mul_i32 s30, s30, s31
	s_mul_hi_u32 s30, s31, s30
	s_add_i32 s31, s31, s30
	s_mul_hi_u32 s30, s29, s31
	s_mul_i32 s31, s30, s28
	s_sub_i32 s29, s29, s31
	s_add_i32 s31, s30, 1
	s_sub_i32 s36, s29, s28
	s_cmp_ge_u32 s29, s28
	s_cselect_b32 s30, s31, s30
	s_cselect_b32 s29, s36, s29
	s_add_i32 s31, s30, 1
	s_cmp_ge_u32 s29, s28
	s_cselect_b32 s28, s31, s30
	s_xor_b32 s28, s28, s17
	s_sub_i32 s52, s28, s17
	s_mul_i32 s17, s52, s23
	s_sub_i32 s16, s16, s17
	s_add_i32 s56, s16, s22
.Lnext_done_28037:
.LBB0_982:
	s_ashr_i32 s57, s56, 31
	s_lshl_b64 s[16:17], s[56:57], 19
	s_add_u32 s58, s20, s16
	s_addc_u32 s59, s21, s17
	s_ashr_i32 s53, s52, 31
	s_lshl_b64 s[16:17], s[52:53], 19
	s_add_u32 s64, s75, s16
	v_cmp_lt_i64_e64 s[12:13], s[12:13], v[170:171]
	s_addc_u32 s65, s76, s17
	s_andn2_b64 vcc, exec, s[50:51]
	s_cbranch_vccnz .Lkzero_984
	s_and_b64 s[16:17], s[12:13], exec
	s_cselect_b32 s53, s59, s27
	s_cselect_b32 s57, s58, s26
	s_cselect_b32 s94, s65, s25
	s_cselect_b32 s95, s64, s24
	s_add_u32 s96, s26, 0x100
	s_addc_u32 s97, s27, 0
	s_add_u32 vcc_lo, s24, 0x100
	s_addc_u32 vcc_hi, s25, 0
	s_mov_b32 s16, 0
	ds_read_b128 v[76:79], v193
	ds_read_b128 v[88:91], v193 offset:1024
	ds_read_b128 v[92:95], v193 offset:2048
	ds_read_b128 v[128:131], v193 offset:3072
	s_add_i32 s22, s16, 2
	s_cmp_eq_u32 s90, s16
	s_cselect_b32 s36, s57, s96
	s_cselect_b32 s26, s53, s97
	s_cselect_b32 s25, s94, vcc_hi
	s_cselect_b32 s28, s95, vcc_lo
	s_add_u32 s24, s36, 0x80
	s_addc_u32 s23, s26, 0
	s_add_u32 s16, s96, s44
	s_addc_u32 s17, s97, s45
	s_add_u32 s16, s16, 0xffffff80
	s_addc_u32 s17, s17, -1
	s_and_b32 s17, s17, 0xffff
	s_mov_b32 m0, s91
	ds_read_b128 v[132:135], v194
	ds_read_b128 v[136:139], v194 offset:1024
	ds_read_b128 v[140:143], v194 offset:2048
	ds_read_b128 v[174:177], v194 offset:3072
	ds_read_b128 v[178:181], v194 offset:4096
	ds_read_b128 v[182:185], v194 offset:5120
	ds_read_b128 v[202:205], v194 offset:6144
	ds_read_b128 v[206:209], v194 offset:7168
	buffer_load_dwordx4 v186, s[16:19], 0 offen lds
	s_mov_b32 m0, s92
	s_nop 0
	buffer_load_dwordx4 v188, s[16:19], 0 offen lds
	s_waitcnt lgkmcnt(8)
	s_barrier
	s_waitcnt lgkmcnt(0)
	s_setprio 1
	s_waitcnt lgkmcnt(7)
	v_mfma_f32_16x16x32_bf16 v[152:155], v[76:79], v[132:135], 0
	v_mfma_f32_16x16x32_bf16 v[144:147], v[92:95], v[132:135], 0
	s_waitcnt lgkmcnt(5)
	v_mfma_f32_16x16x32_bf16 v[124:127], v[76:79], v[140:143], 0
	v_mfma_f32_16x16x32_bf16 v[120:123], v[92:95], v[140:143], 0
	s_waitcnt lgkmcnt(3)
	v_mfma_f32_16x16x32_bf16 v[108:111], v[76:79], v[178:181], 0
	v_mfma_f32_16x16x32_bf16 v[104:107], v[92:95], v[178:181], 0
	s_waitcnt lgkmcnt(1)
	v_mfma_f32_16x16x32_bf16 v[84:87], v[76:79], v[202:205], 0
	v_mfma_f32_16x16x32_bf16 v[80:83], v[92:95], v[202:205], 0
	v_mfma_f32_16x16x32_bf16 v[152:155], v[88:91], v[136:139], v[152:155]
	v_mfma_f32_16x16x32_bf16 v[144:147], v[128:131], v[136:139], v[144:147]
	v_mfma_f32_16x16x32_bf16 v[124:127], v[88:91], v[174:177], v[124:127]
	v_mfma_f32_16x16x32_bf16 v[120:123], v[128:131], v[174:177], v[120:123]
	v_mfma_f32_16x16x32_bf16 v[108:111], v[88:91], v[182:185], v[108:111]
	v_mfma_f32_16x16x32_bf16 v[104:107], v[128:131], v[182:185], v[104:107]
	s_waitcnt lgkmcnt(0)
	v_mfma_f32_16x16x32_bf16 v[84:87], v[88:91], v[206:209], v[84:87]
	v_mfma_f32_16x16x32_bf16 v[80:83], v[128:131], v[206:209], v[80:83]
	s_setprio 0
	s_barrier
; #define PG8_STAGE(bufoff, gbase, voff) do { const __amdgpu_buffer_rsrc_t _r = __builtin_amdgcn_make_buffer_rsrc((void*)(gbase), (short)0, 0x7fffffff, 0x00020000); _Pragma("unroll") for (int _i = 0; _i < 2; ++_i) \
;         __builtin_amdgcn_raw_ptr_buffer_load_lds(_r, (LAS unsigned*)(lds + (bufoff) + ldsw + _i * 8192), 16, (int)(voff)[_i], 0, 0, 0); } while (0)
; #define PG8_LDA(dst, b, h) do { _Pragma("unroll") for (int m = 0; m < 4; ++m) _Pragma("unroll") for (int k = 0; k < 2; ++k) dst[m][k] = *(const LAS bf16x8*)(lds + PG8_SA(b, h) + aoff + m * 2048 + k * 1024); } while (0)
; #define PG8_LDB(dst, b, h) do { _Pragma("unroll") for (int n = 0; n < 2; ++n) _Pragma("unroll") for (int k = 0; k < 2; ++k) dst[n][k] = *(const LAS bf16x8*)(lds + PG8_SB(b, h) + boff + n * 2048 + k * 1024); } while (0)
; #define PG8_MMA(ai, bj, At, Bt) do { __builtin_amdgcn_s_setprio(1); _Pragma("unroll") for (int k = 0; k < 2; ++k) _Pragma("unroll") for (int m = 0; m < 4; ++m) _Pragma("unroll") for (int n = 0; n < ((bj) == 1 ? NB1 : 2); ++n) \
;         acc[ai][bj][m][n] = __builtin_amdgcn_mfma_f32_16x16x32_bf16(Bt[n][k], At[m][k], acc[ai][bj][m][n], 0, 0, 0); __builtin_amdgcn_s_setprio(0); } while (0)
; #define PG8_WAIT_V(n) asm volatile("s_waitcnt vmcnt(" #n ")" ::: "memory")
; #define PG8_WAIT_L(n) asm volatile("s_waitcnt lgkmcnt(" #n ")" ::: "memory")
;     ...
;             PG8_LDB(B1, 0, 1); PG8_STAGE(PG8_SB(0, 0), b2, voffB);
;             PG8_BAR; PG8_WAIT_L(0); PG8_MMA(0, 1, At, B1); PG8_BAR;
;             PG8_LDA(At, 0, 1); PG8_STAGE(PG8_SA(0, 0), a2, voffA);
;             PG8_BAR; PG8_WAIT_L(0); PG8_MMA(1, 0, At, B0); PG8_BAR; PG8_SCHED;
;             PG8_STAGE(PG8_SB(0, 1), b2 + hstepB, voffB);
;             PG8_WAIT_V(6); PG8_BAR; PG8_MMA(1, 1, At, B1); PG8_BAR;
;             PG8_LDB(B0, 1, 0); PG8_SCHED; PG8_LDA(At, 1, 0); PG8_STAGE(PG8_SA(0, 1), a2 + hstepA, voffA);
;             PG8_WAIT_L(8); PG8_BAR; PG8_WAIT_L(0); PG8_MMA(0, 0, At, B0); PG8_BAR; PG8_SCHED;
;             PG8_LDB(B1, 1, 1); PG8_STAGE(PG8_SB(1, 0), b3, voffB);
;             PG8_BAR; PG8_WAIT_L(0); PG8_MMA(0, 1, At, B1); PG8_BAR;
;             PG8_LDA(At, 1, 1); PG8_STAGE(PG8_SA(1, 0), a3, voffA);
;             PG8_BAR; PG8_WAIT_L(0); PG8_MMA(1, 0, At, B0); PG8_BAR; PG8_SCHED;
;             PG8_STAGE(PG8_SB(1, 1), b3 + hstepB, voffB);
;             PG8_WAIT_V(6); PG8_BAR; PG8_MMA(1, 1, At, B1); PG8_BAR;
	s_and_b32 s29, s25, 0xffff
	s_mov_b32 s30, s18
	s_mov_b32 s31, s19
	s_mov_b32 m0, s71
	ds_read_b128 v[210:213], v195
	ds_read_b128 v[214:217], v195 offset:1024
	ds_read_b128 v[218:221], v195 offset:2048
	ds_read_b128 v[222:225], v195 offset:3072
	buffer_load_dwordx4 v187, s[28:31], 0 offen lds
	s_mov_b32 m0, s77
	s_nop 0
	buffer_load_dwordx4 v189, s[28:31], 0 offen lds
	s_barrier
	s_waitcnt lgkmcnt(0)
	s_setprio 1
	s_waitcnt lgkmcnt(3)
	v_mfma_f32_16x16x32_bf16 v[116:119], v[210:213], v[140:143], 0
	s_waitcnt lgkmcnt(1)
	v_mfma_f32_16x16x32_bf16 v[112:115], v[218:221], v[140:143], 0
	v_mfma_f32_16x16x32_bf16 v[100:103], v[210:213], v[178:181], 0
	v_mfma_f32_16x16x32_bf16 v[96:99], v[218:221], v[178:181], 0
	v_mfma_f32_16x16x32_bf16 v[68:71], v[210:213], v[202:205], 0
	v_mfma_f32_16x16x32_bf16 v[64:67], v[218:221], v[202:205], 0
	v_mfma_f32_16x16x32_bf16 v[156:159], v[210:213], v[132:135], 0
	v_mfma_f32_16x16x32_bf16 v[132:135], v[218:221], v[132:135], 0
	v_mfma_f32_16x16x32_bf16 v[116:119], v[214:217], v[174:177], v[116:119]
	s_waitcnt lgkmcnt(0)
	v_mfma_f32_16x16x32_bf16 v[112:115], v[222:225], v[174:177], v[112:115]
	v_mfma_f32_16x16x32_bf16 v[100:103], v[214:217], v[182:185], v[100:103]
	v_mfma_f32_16x16x32_bf16 v[96:99], v[222:225], v[182:185], v[96:99]
	v_mfma_f32_16x16x32_bf16 v[68:71], v[214:217], v[206:209], v[68:71]
	v_mfma_f32_16x16x32_bf16 v[64:67], v[222:225], v[206:209], v[64:67]
	v_mfma_f32_16x16x32_bf16 v[140:143], v[214:217], v[136:139], v[156:159]
	v_mfma_f32_16x16x32_bf16 v[132:135], v[222:225], v[136:139], v[132:135]
	s_setprio 0
	s_and_b32 s37, s26, 0xffff
	s_mov_b32 s38, s18
	s_mov_b32 s39, s19
	s_mov_b32 m0, s67
	s_barrier
	ds_read_b128 v[136:139], v194 offset:16384
	ds_read_b128 v[148:151], v194 offset:17408
	ds_read_b128 v[156:159], v194 offset:18432
	ds_read_b128 v[174:177], v194 offset:19456
	ds_read_b128 v[178:181], v194 offset:20480
	ds_read_b128 v[182:185], v194 offset:21504
	ds_read_b128 v[202:205], v194 offset:22528
	ds_read_b128 v[206:209], v194 offset:23552
	buffer_load_dwordx4 v186, s[36:39], 0 offen lds
	s_mov_b32 m0, s78
	s_nop 0
	buffer_load_dwordx4 v188, s[36:39], 0 offen lds
	s_barrier
	s_waitcnt lgkmcnt(0)
	s_setprio 1
	s_waitcnt lgkmcnt(7)
	v_mfma_f32_16x16x32_bf16 v[60:63], v[76:79], v[136:139], 0
	v_mfma_f32_16x16x32_bf16 v[52:55], v[92:95], v[136:139], 0
	s_waitcnt lgkmcnt(5)
	v_mfma_f32_16x16x32_bf16 v[44:47], v[76:79], v[156:159], 0
	v_mfma_f32_16x16x32_bf16 v[40:43], v[92:95], v[156:159], 0
	s_waitcnt lgkmcnt(3)
	v_mfma_f32_16x16x32_bf16 v[28:31], v[76:79], v[178:181], 0
	v_mfma_f32_16x16x32_bf16 v[24:27], v[92:95], v[178:181], 0
	s_waitcnt lgkmcnt(1)
	v_mfma_f32_16x16x32_bf16 v[12:15], v[76:79], v[202:205], 0
	v_mfma_f32_16x16x32_bf16 v[8:11], v[92:95], v[202:205], 0
	v_mfma_f32_16x16x32_bf16 v[60:63], v[88:91], v[148:151], v[60:63]
	v_mfma_f32_16x16x32_bf16 v[52:55], v[128:131], v[148:151], v[52:55]
	v_mfma_f32_16x16x32_bf16 v[44:47], v[88:91], v[174:177], v[44:47]
	v_mfma_f32_16x16x32_bf16 v[40:43], v[128:131], v[174:177], v[40:43]
	v_mfma_f32_16x16x32_bf16 v[28:31], v[88:91], v[182:185], v[28:31]
	v_mfma_f32_16x16x32_bf16 v[24:27], v[128:131], v[182:185], v[24:27]
	s_waitcnt lgkmcnt(0)
	v_mfma_f32_16x16x32_bf16 v[12:15], v[88:91], v[206:209], v[12:15]
	v_mfma_f32_16x16x32_bf16 v[8:11], v[128:131], v[206:209], v[8:11]
	s_setprio 0
	s_barrier
	s_add_u32 s16, s28, s46
	s_addc_u32 s14, s25, s47
	s_and_b32 s17, s14, 0xffff
	s_mov_b32 m0, s79
	s_nop 0
	buffer_load_dwordx4 v187, s[16:19], 0 offen lds
	s_mov_b32 m0, s80
	s_nop 0
	buffer_load_dwordx4 v189, s[16:19], 0 offen lds
	s_waitcnt vmcnt(6)
	s_barrier
	s_setprio 1
	v_mfma_f32_16x16x32_bf16 v[56:59], v[210:213], v[136:139], 0
	v_mfma_f32_16x16x32_bf16 v[48:51], v[218:221], v[136:139], 0
	v_mfma_f32_16x16x32_bf16 v[36:39], v[210:213], v[156:159], 0
	v_mfma_f32_16x16x32_bf16 v[32:35], v[218:221], v[156:159], 0
	v_mfma_f32_16x16x32_bf16 v[20:23], v[210:213], v[178:181], 0
	v_mfma_f32_16x16x32_bf16 v[16:19], v[218:221], v[178:181], 0
	v_mfma_f32_16x16x32_bf16 v[4:7], v[210:213], v[202:205], 0
	v_mfma_f32_16x16x32_bf16 v[0:3], v[218:221], v[202:205], 0
	v_mfma_f32_16x16x32_bf16 v[56:59], v[214:217], v[148:151], v[56:59]
	v_mfma_f32_16x16x32_bf16 v[48:51], v[222:225], v[148:151], v[48:51]
	v_mfma_f32_16x16x32_bf16 v[36:39], v[214:217], v[174:177], v[36:39]
	v_mfma_f32_16x16x32_bf16 v[32:35], v[222:225], v[174:177], v[32:35]
	v_mfma_f32_16x16x32_bf16 v[20:23], v[214:217], v[182:185], v[20:23]
	v_mfma_f32_16x16x32_bf16 v[16:19], v[222:225], v[182:185], v[16:19]
	v_mfma_f32_16x16x32_bf16 v[4:7], v[214:217], v[206:209], v[4:7]
	v_mfma_f32_16x16x32_bf16 v[0:3], v[222:225], v[206:209], v[0:3]
	s_setprio 0
	s_barrier
	s_branch .Lkmid_984
